# baseline (speedup 1.0000x reference)
.LBB0_391:
	s_nop 9
	v_max_f32_e32 v3, v99, v99
	v_max_f32_e32 v4, v98, v98
	v_max_f32_e32 v3, v4, v3
	v_max3_f32 v3, v3, v100, v101
	v_max3_f32 v3, v3, v102, v103
	v_max3_f32 v3, v3, v104, v105
	v_max3_f32 v3, v3, v106, v107
	v_max3_f32 v3, v3, v108, v109
	v_max3_f32 v3, v3, v110, v111
	v_max3_f32 v3, v3, v112, v113
	v_max3_f32 v3, v3, v82, v83
	v_max3_f32 v3, v3, v84, v85
	v_max3_f32 v3, v3, v86, v87
	v_max3_f32 v3, v3, v88, v89
	v_max3_f32 v3, v3, v90, v91
	v_max3_f32 v3, v3, v92, v93
	v_max3_f32 v3, v3, v94, v95
	v_max3_f32 v3, v3, v96, v97
	v_mov_b32_e32 v4, v3
	s_nop 1
	v_permlane32_swap_b32_e32 v3, v4
	v_max_f32_e32 v4, v4, v4
	v_max_f32_e32 v3, v3, v3
	v_max_f32_e32 v3, v3, v4
	v_sub_f32_e32 v4, v3, v232
	v_mul_f32_e32 v4, 0x3d93cd3a, v4
	v_cmp_ge_f32_e32 vcc, s96, v4
	v_max_f32_e32 v5, v232, v232
	s_cmp_eq_u64 vcc, exec
	v_max_f32_e32 v5, v5, v3
	s_cselect_b64 vcc, -1, 0
	v_sub_f32_e32 v3, v232, v5
	v_cndmask_b32_e32 v232, v5, v232, vcc
	v_mul_f32_e32 v4, 0xbdd53b94, v232
	v_fmamk_f32 v5, v98, 0x3dd53b94, v4
	v_fmamk_f32 v6, v99, 0x3dd53b94, v4
	v_exp_f32_e32 v5, v5
	v_fmamk_f32 v7, v100, 0x3dd53b94, v4
	v_exp_f32_e32 v6, v6
	v_fmamk_f32 v8, v101, 0x3dd53b94, v4
	v_exp_f32_e32 v7, v7
	v_fmamk_f32 v9, v102, 0x3dd53b94, v4
	v_fmamk_f32 v10, v103, 0x3dd53b94, v4
	v_fmamk_f32 v11, v104, 0x3dd53b94, v4
	v_fmamk_f32 v12, v105, 0x3dd53b94, v4
	v_fmamk_f32 v13, v106, 0x3dd53b94, v4
	v_fmamk_f32 v14, v107, 0x3dd53b94, v4
	v_fmamk_f32 v15, v108, 0x3dd53b94, v4
	v_fmamk_f32 v16, v109, 0x3dd53b94, v4
	v_fmamk_f32 v17, v110, 0x3dd53b94, v4
	v_fmamk_f32 v98, v111, 0x3dd53b94, v4
	v_fmamk_f32 v99, v112, 0x3dd53b94, v4
	v_fmamk_f32 v100, v113, 0x3dd53b94, v4
	v_fmamk_f32 v82, v82, 0x3dd53b94, v4
	v_fmamk_f32 v83, v83, 0x3dd53b94, v4
	v_fmamk_f32 v84, v84, 0x3dd53b94, v4
	v_fmamk_f32 v85, v85, 0x3dd53b94, v4
	v_fmamk_f32 v86, v86, 0x3dd53b94, v4
	v_fmamk_f32 v87, v87, 0x3dd53b94, v4
	v_fmamk_f32 v88, v88, 0x3dd53b94, v4
	v_fmamk_f32 v89, v89, 0x3dd53b94, v4
	v_fmamk_f32 v90, v90, 0x3dd53b94, v4
	v_fmamk_f32 v91, v91, 0x3dd53b94, v4
	v_fmamk_f32 v92, v92, 0x3dd53b94, v4
	v_fmamk_f32 v93, v93, 0x3dd53b94, v4
	v_fmamk_f32 v94, v94, 0x3dd53b94, v4
	v_fmamk_f32 v95, v95, 0x3dd53b94, v4
	v_fmamk_f32 v96, v96, 0x3dd53b94, v4
	v_fmac_f32_e32 v4, 0x3dd53b94, v97
	v_exp_f32_e32 v8, v8
	v_exp_f32_e32 v9, v9
	v_exp_f32_e32 v102, v4
	v_add_f32_e32 v4, 0, v5
	v_exp_f32_e32 v10, v10
	v_add_f32_e32 v4, v6, v4
	v_exp_f32_e32 v11, v11
	v_add_f32_e32 v4, v7, v4
	v_exp_f32_e32 v12, v12
	v_add_f32_e32 v4, v8, v4
	v_exp_f32_e32 v13, v13
	v_add_f32_e32 v4, v9, v4
	v_exp_f32_e32 v14, v14
	v_add_f32_e32 v4, v10, v4
	v_exp_f32_e32 v15, v15
	v_add_f32_e32 v4, v11, v4
	v_exp_f32_e32 v97, v16
	v_add_f32_e32 v4, v12, v4
	v_exp_f32_e32 v101, v17
	v_add_f32_e32 v4, v13, v4
	v_exp_f32_e32 v98, v98
	v_add_f32_e32 v4, v14, v4
	v_exp_f32_e32 v99, v99
	v_add_f32_e32 v4, v15, v4
	v_exp_f32_e32 v100, v100
	v_add_f32_e32 v4, v97, v4
	v_exp_f32_e32 v82, v82
	v_add_f32_e32 v4, v101, v4
	v_exp_f32_e32 v83, v83
	v_add_f32_e32 v4, v98, v4
	v_exp_f32_e32 v84, v84
	v_add_f32_e32 v4, v99, v4
	v_exp_f32_e32 v85, v85
	v_add_f32_e32 v4, v100, v4
	v_exp_f32_e32 v86, v86
	v_add_f32_e32 v4, v82, v4
	v_exp_f32_e32 v87, v87
	v_add_f32_e32 v4, v83, v4
	v_exp_f32_e32 v88, v88
	v_add_f32_e32 v4, v84, v4
	v_exp_f32_e32 v89, v89
	v_add_f32_e32 v4, v85, v4
	v_exp_f32_e32 v90, v90
	v_add_f32_e32 v4, v86, v4
	v_exp_f32_e32 v91, v91
	v_add_f32_e32 v4, v87, v4
	v_exp_f32_e32 v92, v92
	v_add_f32_e32 v4, v88, v4
	v_exp_f32_e32 v93, v93
	v_add_f32_e32 v4, v89, v4
	v_exp_f32_e32 v94, v94
	v_add_f32_e32 v4, v90, v4
	v_exp_f32_e32 v95, v95
	v_add_f32_e32 v4, v91, v4
	v_exp_f32_e32 v96, v96
	v_add_f32_e32 v4, v92, v4
	v_mul_f32_e32 v3, 0x3dd53b94, v3
	v_add_f32_e32 v4, v93, v4
	v_exp_f32_e32 v3, v3
	v_add_f32_e32 v4, v94, v4
	v_add_f32_e32 v4, v95, v4
	v_add_f32_e32 v4, v96, v4
	v_add_f32_e32 v16, v102, v4
	v_cndmask_b32_e64 v3, v3, 1.0, vcc
	v_mov_b32_e32 v17, v16
	v_cvt_pk_bf16_f32 v4, v5, v6
	v_cvt_pk_bf16_f32 v5, v7, v8
	v_cvt_pk_bf16_f32 v6, v9, v10
	v_cvt_pk_bf16_f32 v7, v11, v12
	v_cvt_pk_bf16_f32 v8, v13, v14
	v_cvt_pk_bf16_f32 v9, v15, v97
	v_cvt_pk_bf16_f32 v10, v101, v98
	v_cvt_pk_bf16_f32 v11, v99, v100
	v_cvt_pk_bf16_f32 v12, v82, v83
	v_cvt_pk_bf16_f32 v13, v84, v85
	v_cvt_pk_bf16_f32 v14, v86, v87
	v_cvt_pk_bf16_f32 v15, v88, v89
	v_cvt_pk_bf16_f32 v82, v90, v91
	v_cvt_pk_bf16_f32 v83, v92, v93
	v_cvt_pk_bf16_f32 v84, v94, v95
	v_cvt_pk_bf16_f32 v85, v96, v102
	s_nop 1
	v_permlane32_swap_b32_e32 v16, v17
	v_permlane32_swap_b32_e32 v4, v6
	v_permlane32_swap_b32_e32 v5, v7
	v_permlane32_swap_b32_e32 v8, v10
	v_permlane32_swap_b32_e32 v9, v11
	v_permlane32_swap_b32_e32 v12, v14
	v_permlane32_swap_b32_e32 v13, v15
	v_permlane32_swap_b32_e32 v82, v84
	v_permlane32_swap_b32_e32 v83, v85
	v_cmp_gt_f32_e32 vcc, 1.0, v3
	s_cbranch_vccz .LBB0_395
	s_and_saveexec_b64 s[8:9], s[6:7]
	ds_write_b32 v226, v3 offset:128
	s_or_b64 exec, exec, s[8:9]
	s_waitcnt lgkmcnt(0)
	ds_read_b128 v[86:89], v214 offset:224
	ds_read_b128 v[90:93], v214 offset:192
	ds_read_b128 v[94:97], v214 offset:160
	ds_read_b128 v[98:101], v214 offset:128
	s_waitcnt lgkmcnt(3)
	v_pk_mul_f32 v[80:81], v[80:81], v[88:89]
	s_waitcnt lgkmcnt(2)
	v_pk_mul_f32 v[76:77], v[76:77], v[92:93]
	s_waitcnt lgkmcnt(1)
	v_pk_mul_f32 v[72:73], v[72:73], v[96:97]
	s_waitcnt lgkmcnt(0)
	v_pk_mul_f32 v[68:69], v[68:69], v[100:101]
	v_pk_mul_f32 v[78:79], v[78:79], v[86:87]
	v_pk_mul_f32 v[74:75], v[74:75], v[90:91]
	v_pk_mul_f32 v[70:71], v[70:71], v[94:95]
	v_pk_mul_f32 v[66:67], v[66:67], v[98:99]
	v_pk_mul_f32 v[64:65], v[64:65], v[88:89]
	v_pk_mul_f32 v[60:61], v[60:61], v[92:93]
	v_pk_mul_f32 v[56:57], v[56:57], v[96:97]
	v_pk_mul_f32 v[52:53], v[52:53], v[100:101]
	v_pk_mul_f32 v[62:63], v[62:63], v[86:87]
	v_pk_mul_f32 v[58:59], v[58:59], v[90:91]
	v_pk_mul_f32 v[54:55], v[54:55], v[94:95]
	v_pk_mul_f32 v[50:51], v[50:51], v[98:99]
	v_pk_mul_f32 v[48:49], v[48:49], v[88:89]
	v_pk_mul_f32 v[44:45], v[44:45], v[92:93]
	v_pk_mul_f32 v[40:41], v[40:41], v[96:97]
	v_pk_mul_f32 v[36:37], v[36:37], v[100:101]
	v_pk_mul_f32 v[46:47], v[46:47], v[86:87]
	v_pk_mul_f32 v[42:43], v[42:43], v[90:91]
	v_pk_mul_f32 v[38:39], v[38:39], v[94:95]
	v_pk_mul_f32 v[34:35], v[34:35], v[98:99]
	v_pk_mul_f32 v[32:33], v[32:33], v[88:89]
	v_pk_mul_f32 v[28:29], v[28:29], v[92:93]
	v_pk_mul_f32 v[24:25], v[24:25], v[96:97]
	v_pk_mul_f32 v[20:21], v[20:21], v[100:101]
	v_pk_mul_f32 v[30:31], v[30:31], v[86:87]
	v_pk_mul_f32 v[26:27], v[26:27], v[90:91]
	v_pk_mul_f32 v[22:23], v[22:23], v[94:95]
	v_pk_mul_f32 v[18:19], v[18:19], v[98:99]
